# pooling item: the eight dependent weight-staging round trips (4 loops x 2 trips) issued together; pool and chunk staging ladders de-serialized
# speedup vs baseline: 1.0321x; 1.0136x over previous
.LBB0_612:
	s_and_b64 vcc, exec, s[0:1]
	s_cbranch_vccz .LBB0_711
	s_add_i32 s0, s20, 0xffffff00
	s_lshl_b32 s21, s0, 5
	s_cmpk_lt_u32 s0, 0x80
	s_movk_i32 s1, 0xe0
	s_movk_i32 s0, 0x1f00
	s_cselect_b32 s1, s1, 0x3e0
	s_movk_i32 s4, 0x400
	v_mov_b32_e32 v1, v0
	s_cselect_b32 s0, s0, 0x1c00
	s_cselect_b32 s23, 0x100, s4
	s_and_b32 s22, s1, s21
	s_add_i32 s5, s22, -8
	v_lshlrev_b32_e32 v2, 2, v1
	s_waitcnt vmcnt(9)
	v_ashrrev_i32_e32 v9, 6, v1
	v_and_b32_e32 v3, 0xfc, v2
	v_add_u32_e32 v8, s5, v9
	s_and_b32 s4, s0, s21
	v_cmp_gt_u32_e32 vcc, s23, v8
	v_mov_b32_e32 v2, 0
	v_lshlrev_b32_e32 v130, 2, v3
	v_mov_b32_e32 v4, 0
	v_mov_b32_e32 v5, 0
	v_mov_b32_e32 v6, 0
	v_mov_b32_e32 v7, 0
	s_barrier
	v_mov_b32_e32 v10, 0
	v_mov_b32_e32 v11, 0
	v_mov_b32_e32 v12, 0
	v_mov_b32_e32 v13, 0
	v_mov_b32_e32 v14, 0
	v_mov_b32_e32 v15, 0
	v_mov_b32_e32 v16, 0
	v_mov_b32_e32 v17, 0
	v_mov_b32_e32 v18, 0
	v_mov_b32_e32 v19, 0
	v_mov_b32_e32 v20, 0
	v_mov_b32_e32 v21, 0
	v_mov_b32_e32 v22, 0
	v_mov_b32_e32 v23, 0
	v_mov_b32_e32 v24, 0
	v_mov_b32_e32 v25, 0
	v_mov_b32_e32 v26, 0
	v_mov_b32_e32 v27, 0
	v_mov_b32_e32 v28, 0
	v_mov_b32_e32 v29, 0
	v_lshl_add_u32 v30, v3, 2, v212
	v_lshl_add_u32 v30, v9, 10, v30
	v_add_u32_e32 v31, s5, v9
	v_cmp_gt_u32_e32 vcc, s23, v31
	s_and_saveexec_b64 s[0:1], vcc
	s_cbranch_execz .Lpool_sk0
	v_add_u32_e32 v32, s4, v31
	v_mov_b64_e32 v[2:3], s[18:19]
	v_mad_u64_u32 v[2:3], s[6:7], v32, s36, v[2:3]
	v_lshl_add_u64 v[2:3], v[2:3], 0, v[130:131]
	v_add_co_u32_e32 v2, vcc, 0x34a5000, v2
	s_nop 1
	v_addc_co_u32_e32 v3, vcc, 0, v3, vcc
	global_load_dwordx4 v[4:7], v[2:3], off offset:1280
.Lpool_sk0:
	s_or_b64 exec, exec, s[0:1]
	v_add_u32_e32 v31, s5, v9
	v_add_u32_e32 v31, 8, v31
	v_cmp_gt_u32_e32 vcc, s23, v31
	s_and_saveexec_b64 s[0:1], vcc
	s_cbranch_execz .Lpool_sk1
	v_add_u32_e32 v32, s4, v31
	v_mov_b64_e32 v[2:3], s[18:19]
	v_mad_u64_u32 v[2:3], s[6:7], v32, s36, v[2:3]
	v_lshl_add_u64 v[2:3], v[2:3], 0, v[130:131]
	v_add_co_u32_e32 v2, vcc, 0x34a5000, v2
	s_nop 1
	v_addc_co_u32_e32 v3, vcc, 0, v3, vcc
	global_load_dwordx4 v[10:13], v[2:3], off offset:1280
.Lpool_sk1:
	s_or_b64 exec, exec, s[0:1]
	v_add_u32_e32 v31, s5, v9
	v_add_u32_e32 v31, 16, v31
	v_cmp_gt_u32_e32 vcc, s23, v31
	s_and_saveexec_b64 s[0:1], vcc
	s_cbranch_execz .Lpool_sk2
	v_add_u32_e32 v32, s4, v31
	v_mov_b64_e32 v[2:3], s[18:19]
	v_mad_u64_u32 v[2:3], s[6:7], v32, s36, v[2:3]
	v_lshl_add_u64 v[2:3], v[2:3], 0, v[130:131]
	v_add_co_u32_e32 v2, vcc, 0x34a5000, v2
	s_nop 1
	v_addc_co_u32_e32 v3, vcc, 0, v3, vcc
	global_load_dwordx4 v[14:17], v[2:3], off offset:1280
.Lpool_sk2:
	s_or_b64 exec, exec, s[0:1]
	v_add_u32_e32 v31, s5, v9
	v_add_u32_e32 v31, 24, v31
	v_cmp_gt_u32_e32 vcc, s23, v31
	s_and_saveexec_b64 s[0:1], vcc
	s_cbranch_execz .Lpool_sk3
	v_add_u32_e32 v32, s4, v31
	v_mov_b64_e32 v[2:3], s[18:19]
	v_mad_u64_u32 v[2:3], s[6:7], v32, s36, v[2:3]
	v_lshl_add_u64 v[2:3], v[2:3], 0, v[130:131]
	v_add_co_u32_e32 v2, vcc, 0x34a5000, v2
	s_nop 1
	v_addc_co_u32_e32 v3, vcc, 0, v3, vcc
	global_load_dwordx4 v[18:21], v[2:3], off offset:1280
.Lpool_sk3:
	s_or_b64 exec, exec, s[0:1]
	v_add_u32_e32 v31, s5, v9
	v_add_u32_e32 v31, 32, v31
	v_cmp_gt_u32_e32 vcc, s23, v31
	s_and_saveexec_b64 s[0:1], vcc
	s_cbranch_execz .Lpool_sk4
	v_add_u32_e32 v32, s4, v31
	v_mov_b64_e32 v[2:3], s[18:19]
	v_mad_u64_u32 v[2:3], s[6:7], v32, s36, v[2:3]
	v_lshl_add_u64 v[2:3], v[2:3], 0, v[130:131]
	v_add_co_u32_e32 v2, vcc, 0x34a5000, v2
	s_nop 1
	v_addc_co_u32_e32 v3, vcc, 0, v3, vcc
	global_load_dwordx4 v[22:25], v[2:3], off offset:1280
.Lpool_sk4:
	s_or_b64 exec, exec, s[0:1]
	v_add_u32_e32 v31, s5, v9
	v_add_u32_e32 v31, 40, v31
	v_cmp_gt_u32_e32 vcc, s23, v31
	s_and_saveexec_b64 s[0:1], vcc
	s_cbranch_execz .Lpool_sk5
	v_add_u32_e32 v32, s4, v31
	v_mov_b64_e32 v[2:3], s[18:19]
	v_mad_u64_u32 v[2:3], s[6:7], v32, s36, v[2:3]
	v_lshl_add_u64 v[2:3], v[2:3], 0, v[130:131]
	v_add_co_u32_e32 v2, vcc, 0x34a5000, v2
	s_nop 1
	v_addc_co_u32_e32 v3, vcc, 0, v3, vcc
	global_load_dwordx4 v[26:29], v[2:3], off offset:1280
.Lpool_sk5:
	s_or_b64 exec, exec, s[0:1]
	s_waitcnt vmcnt(0)
	ds_write_b128 v30, v[4:7]
	ds_write_b128 v30, v[10:13] offset:8192
	ds_write_b128 v30, v[14:17] offset:16384
	ds_write_b128 v30, v[18:21] offset:24576
	ds_write_b128 v30, v[22:25] offset:32768
	ds_write_b128 v30, v[26:29] offset:40960
	ds_read_b64 v[2:3], v131 offset:184
	v_readlane_b32 s4, v255, 0
	v_readlane_b32 s5, v255, 1
	s_waitcnt lgkmcnt(0)
	v_readfirstlane_b32 s0, v2
	v_readfirstlane_b32 s1, v3
	s_add_u32 s0, s0, s4
	s_addc_u32 s1, s1, s5
	v_readlane_b32 s10, v254, 51
	v_lshrrev_b32_e32 v2, 4, v0
	v_lshlrev_b32_e32 v3, 2, v0
	v_and_b32_e32 v3, 60, v3
	v_lshlrev_b32_e32 v32, 8, v2
	v_lshl_add_u32 v32, v3, 2, v32
	v_add_u32_e32 v130, 0x2000, v32
	v_mul_u32_u24_e32 v33, 0x90, v3
	v_lshl_add_u32 v33, v2, 1, v33
	s_add_u32 s4, s0, 0x4000
	s_addc_u32 s5, s1, 0
	s_add_u32 s6, s0, 0x8000
	s_addc_u32 s7, s1, 0
	s_add_u32 s14, s0, 0xc000
	s_addc_u32 s15, s1, 0
	global_load_dwordx4 v[4:7], v32, s[0:1]
	global_load_dwordx4 v[8:11], v32, s[4:5]
	global_load_dwordx4 v[12:15], v32, s[6:7]
	global_load_dwordx4 v[16:19], v32, s[14:15]
	global_load_dwordx4 v[20:23], v130, s[0:1]
	global_load_dwordx4 v[24:27], v130, s[4:5]
	global_load_dwordx4 v[28:31], v130, s[6:7]
	s_waitcnt vmcnt(6)
	v_add_u32_e32 v2, s79, v33
	v_cvt_pk_bf16_f32 v3, v4, v131
	ds_write_b16 v2, v3 offset:0
	v_cvt_pk_bf16_f32 v3, v5, v131
	ds_write_b16 v2, v3 offset:144
	v_cvt_pk_bf16_f32 v3, v6, v131
	ds_write_b16 v2, v3 offset:288
	v_cvt_pk_bf16_f32 v3, v7, v131
	ds_write_b16 v2, v3 offset:432
	s_nop 0
	global_load_dwordx4 v[4:7], v130, s[14:15]
	s_waitcnt vmcnt(6)
	v_add_u32_e32 v2, s64, v33
	v_cvt_pk_bf16_f32 v3, v8, v131
	ds_write_b16 v2, v3 offset:0
	v_cvt_pk_bf16_f32 v3, v9, v131
	ds_write_b16 v2, v3 offset:144
	v_cvt_pk_bf16_f32 v3, v10, v131
	ds_write_b16 v2, v3 offset:288
	v_cvt_pk_bf16_f32 v3, v11, v131
	ds_write_b16 v2, v3 offset:432
	s_waitcnt vmcnt(5)
	v_add_u32_e32 v2, s10, v33
	v_cvt_pk_bf16_f32 v3, v12, v131
	ds_write_b16 v2, v3 offset:0
	v_cvt_pk_bf16_f32 v3, v13, v131
	ds_write_b16 v2, v3 offset:144
	v_cvt_pk_bf16_f32 v3, v14, v131
	ds_write_b16 v2, v3 offset:288
	v_cvt_pk_bf16_f32 v3, v15, v131
	ds_write_b16 v2, v3 offset:432
	s_waitcnt vmcnt(4)
	v_add_u32_e32 v2, s72, v33
	v_cvt_pk_bf16_f32 v3, v16, v131
	ds_write_b16 v2, v3 offset:0
	v_cvt_pk_bf16_f32 v3, v17, v131
	ds_write_b16 v2, v3 offset:144
	v_cvt_pk_bf16_f32 v3, v18, v131
	ds_write_b16 v2, v3 offset:288
	v_cvt_pk_bf16_f32 v3, v19, v131
	ds_write_b16 v2, v3 offset:432
	s_waitcnt vmcnt(3)
	v_add_u32_e32 v2, s79, v33
	v_cvt_pk_bf16_f32 v3, v20, v131
	ds_write_b16 v2, v3 offset:64
	v_cvt_pk_bf16_f32 v3, v21, v131
	ds_write_b16 v2, v3 offset:208
	v_cvt_pk_bf16_f32 v3, v22, v131
	ds_write_b16 v2, v3 offset:352
	v_cvt_pk_bf16_f32 v3, v23, v131
	ds_write_b16 v2, v3 offset:496
	s_waitcnt vmcnt(2)
	v_add_u32_e32 v2, s64, v33
	v_cvt_pk_bf16_f32 v3, v24, v131
	ds_write_b16 v2, v3 offset:64
	v_cvt_pk_bf16_f32 v3, v25, v131
	ds_write_b16 v2, v3 offset:208
	v_cvt_pk_bf16_f32 v3, v26, v131
	ds_write_b16 v2, v3 offset:352
	v_cvt_pk_bf16_f32 v3, v27, v131
	ds_write_b16 v2, v3 offset:496
	s_waitcnt vmcnt(1)
	v_add_u32_e32 v2, s10, v33
	v_cvt_pk_bf16_f32 v3, v28, v131
	ds_write_b16 v2, v3 offset:64
	v_cvt_pk_bf16_f32 v3, v29, v131
	ds_write_b16 v2, v3 offset:208
	v_cvt_pk_bf16_f32 v3, v30, v131
	ds_write_b16 v2, v3 offset:352
	v_cvt_pk_bf16_f32 v3, v31, v131
	ds_write_b16 v2, v3 offset:496
	s_waitcnt vmcnt(0)
	v_add_u32_e32 v2, s72, v33
	v_cvt_pk_bf16_f32 v3, v4, v131
	ds_write_b16 v2, v3 offset:64
	v_cvt_pk_bf16_f32 v3, v5, v131
	ds_write_b16 v2, v3 offset:208
	v_cvt_pk_bf16_f32 v3, v6, v131
	ds_write_b16 v2, v3 offset:352
	v_cvt_pk_bf16_f32 v3, v7, v131
	ds_write_b16 v2, v3 offset:496
	v_bfe_u32 v3, v1, 6, 2
	v_lshlrev_b32_e64 v4, v3, 2
	v_ashrrev_i32_e32 v5, 4, v1
	v_lshrrev_b32_e32 v3, 1, v4
	v_and_b32_e32 v7, -16, v5
	v_sub_u32_e32 v6, s22, v3
	v_add_u32_e32 v3, v6, v7
	v_add_u32_e32 v8, v3, v4
	v_and_b32_e32 v2, 0xff, v1
	v_max_i32_e32 v9, 0, v3
	v_min_i32_e32 v10, s23, v8
	v_cmp_gt_i32_e32 vcc, v10, v9
	v_mov_b32_e32 v8, 0
	v_lshlrev_b32_e32 v3, 2, v2
	s_waitcnt lgkmcnt(0)
	s_barrier
	s_and_saveexec_b64 s[0:1], vcc
	s_cbranch_execz .LBB0_641
	v_lshl_or_b32 v8, v9, 10, v3
	s_lshl_b32 s4, s22, 10
	v_subrev_u32_e32 v8, s4, v8
	s_add_i32 s4, s73, 0x2000
	v_add_u32_e32 v11, s4, v8
	v_mov_b32_e32 v8, 0
	s_mov_b64 s[4:5], 0
	v_mov_b32_e32 v12, v9
